# retB: nt (streaming) hint on the 18 read-once loads of OFB / gate
# baseline (speedup 1.0000x reference)
.LBB0_405:
	v_ashrrev_i32_e32 v92, 3, v73
	v_ashrrev_i32_e32 v93, 31, v92
	v_lshlrev_b64 v[2:3], 12, v[92:93]
	s_waitcnt vmcnt(24)
	v_and_b32_e32 v8, 0xc00, v94
	v_or_b32_e32 v9, v2, v72
	v_or_b32_e32 v2, v9, v8
	v_lshlrev_b64 v[0:1], 1, v[2:3]
	v_lshl_add_u64 v[4:5], s[44:45], 0, v[0:1]
	v_lshl_add_u64 v[0:1], s[48:49], 0, v[0:1]
	global_load_dwordx4 v[64:67], v[4:5], off nt
	global_load_dwordx4 v[68:71], v[0:1], off nt
	v_mov_b64_e32 v[0:1], s[40:41]
	v_mad_i64_i32 v[4:5], s[4:5], v92, s3, v[0:1]
	s_mov_b64 s[4:5], 0x18e04000
	s_nop 0
	v_lshl_add_u64 v[4:5], v[4:5], 0, s[4:5]
	v_lshlrev_b32_e32 v174, 1, v8
	v_lshl_add_u64 v[6:7], v[4:5], 0, v[174:175]
	v_lshlrev_b32_e32 v74, 1, v72
	v_mov_b32_e32 v75, v175
	v_lshl_add_u64 v[6:7], v[6:7], 0, v[74:75]
	v_or_b32_e32 v8, 0x200, v8
	global_load_dwordx4 v[60:63], v[6:7], off nt
	v_or_b32_e32 v2, v9, v8
	v_lshlrev_b64 v[2:3], 1, v[2:3]
	v_lshl_add_u64 v[6:7], s[44:45], 0, v[2:3]
	v_lshl_add_u64 v[2:3], s[48:49], 0, v[2:3]
	global_load_dwordx4 v[52:55], v[6:7], off nt
	global_load_dwordx4 v[56:59], v[2:3], off nt
	v_lshl_add_u64 v[2:3], v[4:5], 0, v[74:75]
	v_lshlrev_b32_e32 v4, 1, v8
	v_mov_b32_e32 v5, v175
	v_lshl_add_u64 v[2:3], v[2:3], 0, v[4:5]
	global_load_dwordx4 v[48:51], v[2:3], off nt
	v_add_u32_e32 v2, 2, v73
	v_ashrrev_i32_e32 v88, 3, v2
	v_ashrrev_i32_e32 v89, 31, v88
	v_add_u32_e32 v4, 0x400, v94
	v_lshlrev_b64 v[2:3], 12, v[88:89]
	v_and_b32_e32 v6, 0xc00, v4
	v_or_b32_e32 v2, v2, v6
	v_or_b32_e32 v2, v2, v72
	v_lshlrev_b64 v[2:3], 1, v[2:3]
	v_lshl_add_u64 v[4:5], s[44:45], 0, v[2:3]
	v_lshl_add_u64 v[2:3], s[48:49], 0, v[2:3]
	global_load_dwordx4 v[40:43], v[4:5], off nt
	global_load_dwordx4 v[44:47], v[2:3], off nt
	v_mad_i64_i32 v[2:3], s[4:5], v88, s3, v[0:1]
	v_lshlrev_b32_e32 v90, 1, v6
	v_mov_b32_e32 v91, v175
	v_lshl_add_u64 v[2:3], v[2:3], 0, v[90:91]
	v_lshl_add_u64 v[2:3], v[2:3], 0, v[74:75]
	v_add_co_u32_e32 v2, vcc, s22, v2
	v_add_u32_e32 v4, 0x600, v94
	s_nop 0
	v_addc_co_u32_e32 v3, vcc, 0, v3, vcc
	global_load_dwordx4 v[36:39], v[2:3], off nt
	v_add_u32_e32 v2, 3, v73
	v_ashrrev_i32_e32 v84, 3, v2
	v_ashrrev_i32_e32 v85, 31, v84
	v_lshlrev_b64 v[2:3], 12, v[84:85]
	v_and_b32_e32 v6, 0xe00, v4
	v_or_b32_e32 v2, v2, v6
	v_or_b32_e32 v2, v2, v72
	v_lshlrev_b64 v[2:3], 1, v[2:3]
	v_lshl_add_u64 v[4:5], s[44:45], 0, v[2:3]
	v_lshl_add_u64 v[2:3], s[48:49], 0, v[2:3]
	global_load_dwordx4 v[28:31], v[4:5], off nt
	global_load_dwordx4 v[32:35], v[2:3], off nt
	v_mad_i64_i32 v[2:3], s[4:5], v84, s3, v[0:1]
	v_lshlrev_b32_e32 v86, 1, v6
	v_mov_b32_e32 v87, v175
	v_lshl_add_u64 v[2:3], v[2:3], 0, v[86:87]
	v_lshl_add_u64 v[2:3], v[2:3], 0, v[74:75]
	v_add_co_u32_e32 v2, vcc, s22, v2
	v_add_u32_e32 v4, 0x800, v94
	s_nop 0
	v_addc_co_u32_e32 v3, vcc, 0, v3, vcc
	global_load_dwordx4 v[24:27], v[2:3], off nt
	v_add_u32_e32 v2, 4, v73
	v_ashrrev_i32_e32 v80, 3, v2
	v_ashrrev_i32_e32 v81, 31, v80
	v_lshlrev_b64 v[2:3], 12, v[80:81]
	v_and_b32_e32 v6, 0xc00, v4
	v_or_b32_e32 v2, v2, v6
	v_or_b32_e32 v2, v2, v72
	v_lshlrev_b64 v[2:3], 1, v[2:3]
	s_waitcnt vmcnt(10)
	v_lshlrev_b32_e32 v96, 16, v68
	v_lshlrev_b32_e32 v98, 16, v64
	v_lshlrev_b32_e32 v97, 16, v69
	v_lshlrev_b32_e32 v99, 16, v65
	v_lshl_add_u64 v[4:5], s[44:45], 0, v[2:3]
	v_lshl_add_u64 v[2:3], s[48:49], 0, v[2:3]
	v_and_b32_e32 v68, 0xffff0000, v68
	v_and_b32_e32 v64, 0xffff0000, v64
	v_and_b32_e32 v69, 0xffff0000, v69
	v_and_b32_e32 v65, 0xffff0000, v65
	v_pk_add_f32 v[96:97], v[98:99], v[96:97]
	v_lshlrev_b32_e32 v99, 16, v70
	v_lshlrev_b32_e32 v101, 16, v66
	v_lshlrev_b32_e32 v98, 16, v71
	v_lshlrev_b32_e32 v100, 16, v67
	global_load_dwordx4 v[16:19], v[4:5], off nt
	global_load_dwordx4 v[20:23], v[2:3], off nt
	v_mad_i64_i32 v[2:3], s[4:5], v80, s3, v[0:1]
	v_lshlrev_b32_e32 v82, 1, v6
	v_mov_b32_e32 v83, v175
	v_pk_add_f32 v[64:65], v[64:65], v[68:69]
	v_pk_mul_f32 v[68:69], v[96:97], v[96:97]
	v_and_b32_e32 v103, 0xffff0000, v70
	v_and_b32_e32 v105, 0xffff0000, v66
	v_and_b32_e32 v102, 0xffff0000, v71
	v_and_b32_e32 v104, 0xffff0000, v67
	v_pk_add_f32 v[66:67], v[100:101], v[98:99]
	v_lshl_add_u64 v[2:3], v[2:3], 0, v[82:83]
	v_pk_fma_f32 v[68:69], v[64:65], v[64:65], v[68:69]
	v_pk_add_f32 v[70:71], v[104:105], v[102:103]
	v_pk_mul_f32 v[98:99], v[66:67], v[66:67]
	v_lshl_add_u64 v[2:3], v[2:3], 0, v[74:75]
	v_pk_fma_f32 v[98:99], v[70:71], v[70:71], v[98:99]
	v_add_f32_e32 v68, v68, v69
	v_add_co_u32_e32 v2, vcc, s22, v2
	v_add_f32_e32 v68, v99, v68
	s_nop 0
	v_addc_co_u32_e32 v3, vcc, 0, v3, vcc
	v_add_f32_e32 v68, v98, v68
	global_load_dwordx4 v[12:15], v[2:3], off nt
	v_add_u32_e32 v2, 5, v73
	v_add_f32_dpp v68, v68, v68 row_ror:8 row_mask:0xf bank_mask:0xf bound_ctrl:1
	v_ashrrev_i32_e32 v78, 3, v2
	v_ashrrev_i32_e32 v79, 31, v78
	v_add_f32_dpp v68, v68, v68 row_ror:4 row_mask:0xf bank_mask:0xf bound_ctrl:1
	v_add_u32_e32 v4, 0xa00, v94
	v_lshlrev_b64 v[2:3], 12, v[78:79]
	v_add_f32_dpp v68, v68, v68 row_ror:2 row_mask:0xf bank_mask:0xf bound_ctrl:1
	v_and_b32_e32 v76, 0xe00, v4
	v_or_b32_e32 v2, v2, v76
	v_add_f32_dpp v68, v68, v68 row_ror:1 row_mask:0xf bank_mask:0xf bound_ctrl:1
	v_mad_i64_i32 v[0:1], s[4:5], v78, s3, v[0:1]
	v_lshlrev_b32_e32 v76, 1, v76
	v_mov_b32_e32 v77, v175
	v_readlane_b32 s1, v68, 16
	v_readlane_b32 s2, v68, 48
	v_lshl_add_u64 v[0:1], v[0:1], 0, v[76:77]
	v_readlane_b32 s4, v68, 0
	v_readlane_b32 s5, v68, 32
	v_mov_b32_e32 v68, s1
	v_mov_b32_e32 v69, s2
	v_lshl_add_u64 v[0:1], v[0:1], 0, v[74:75]
	v_pk_add_f32 v[68:69], s[4:5], v[68:69]
	v_add_co_u32_e32 v0, vcc, s22, v0
	v_add_f32_e32 v68, v68, v69
	s_nop 0
	v_addc_co_u32_e32 v1, vcc, 0, v1, vcc
	v_fmamk_f32 v68, v68, 0x3b000000, v173
	v_cmp_gt_f32_e32 vcc, s19, v68
	v_mul_f32_e32 v69, 0x4f800000, v68
	v_or_b32_e32 v2, v2, v72
	v_cndmask_b32_e32 v68, v68, v69, vcc
	v_sqrt_f32_e32 v69, v68
	v_lshlrev_b64 v[2:3], 1, v[2:3]
	v_lshl_add_u64 v[4:5], s[44:45], 0, v[2:3]
	v_lshl_add_u64 v[2:3], s[48:49], 0, v[2:3]
	v_add_u32_e32 v95, -1, v69
	v_fma_f32 v98, -v95, v69, v68
	v_cmp_ge_f32_e64 s[38:39], 0, v98
	v_add_u32_e32 v98, 1, v69
	global_load_dwordx4 v[4:7], v[4:5], off nt
	v_cndmask_b32_e64 v95, v69, v95, s[38:39]
	v_fma_f32 v69, -v98, v69, v68
	v_cmp_lt_f32_e64 s[38:39], 0, v69
	global_load_dwordx4 v[8:11], v[2:3], off nt
	s_nop 0
	v_cndmask_b32_e64 v69, v95, v98, s[38:39]
	v_mul_f32_e32 v95, 0x37800000, v69
	v_cndmask_b32_e32 v69, v69, v95, vcc
	v_cmp_class_f32_e32 vcc, v68, v244
	global_load_dwordx4 v[0:3], v[0:1], off nt
	s_nop 0
	v_cndmask_b32_e32 v68, v69, v68, vcc
	v_div_scale_f32 v69, s[4:5], v68, v68, 1.0
	v_rcp_f32_e32 v95, v69
	s_nop 0
	v_fma_f32 v98, -v69, v95, 1.0
	v_fmac_f32_e32 v95, v98, v95
	v_div_scale_f32 v98, vcc, 1.0, v68, 1.0
	v_mul_f32_e32 v99, v98, v95
	v_fma_f32 v100, -v69, v99, v98
	v_fmac_f32_e32 v99, v100, v95
	v_fma_f32 v69, -v69, v99, v98
	v_div_fmas_f32 v69, v69, v95, v99
	v_div_fixup_f32 v68, v69, v68, 1.0
	s_waitcnt vmcnt(15)
	v_lshlrev_b32_e32 v69, 16, v60
	v_mul_f32_e32 v95, 0xbfb8aa3b, v69
	v_exp_f32_e32 v95, v95
	v_and_b32_e32 v60, 0xffff0000, v60
	v_add_f32_e32 v95, 1.0, v95
	v_div_scale_f32 v98, s[4:5], v95, v95, v69
	v_rcp_f32_e32 v99, v98
	s_nop 0
	v_fma_f32 v100, -v98, v99, 1.0
	v_fmac_f32_e32 v99, v100, v99
	v_div_scale_f32 v100, vcc, v69, v95, v69
	v_mul_f32_e32 v101, v100, v99
	v_fma_f32 v102, -v98, v101, v100
	v_fmac_f32_e32 v101, v102, v99
	v_fma_f32 v98, -v98, v101, v100
	v_div_fmas_f32 v98, v98, v99, v101
	v_div_fixup_f32 v69, v98, v95, v69
	v_mul_f32_e32 v95, 0xbfb8aa3b, v60
	v_exp_f32_e32 v95, v95
	v_mul_f32_e32 v69, v96, v69
	v_mul_f32_e32 v69, v69, v68
	v_add_f32_e32 v95, 1.0, v95
	v_div_scale_f32 v96, s[4:5], v95, v95, v60
	v_rcp_f32_e32 v98, v96
	s_nop 0
	v_fma_f32 v99, -v96, v98, 1.0
	v_fmac_f32_e32 v98, v99, v98
	v_div_scale_f32 v99, vcc, v60, v95, v60
	v_mul_f32_e32 v100, v99, v98
	v_fma_f32 v101, -v96, v100, v99
	v_fmac_f32_e32 v100, v101, v98
	v_fma_f32 v96, -v96, v100, v99
	v_div_fmas_f32 v96, v96, v98, v100
	v_div_fixup_f32 v60, v96, v95, v60
	v_mul_f32_e32 v60, v64, v60
	v_mul_f32_e32 v60, v60, v68
	v_lshlrev_b32_e32 v64, 16, v61
	v_cvt_pk_bf16_f32 v60, v69, v60
	v_mul_f32_e32 v69, 0xbfb8aa3b, v64
	v_exp_f32_e32 v69, v69
	v_and_b32_e32 v61, 0xffff0000, v61
	v_add_f32_e32 v69, 1.0, v69
	v_div_scale_f32 v95, s[4:5], v69, v69, v64
	v_rcp_f32_e32 v96, v95
	s_nop 0
	v_fma_f32 v98, -v95, v96, 1.0
	v_fmac_f32_e32 v96, v98, v96
	v_div_scale_f32 v98, vcc, v64, v69, v64
	v_mul_f32_e32 v99, v98, v96
	v_fma_f32 v100, -v95, v99, v98
	v_fmac_f32_e32 v99, v100, v96
	v_fma_f32 v95, -v95, v99, v98
	v_div_fmas_f32 v95, v95, v96, v99
	v_div_fixup_f32 v64, v95, v69, v64
	v_mul_f32_e32 v69, 0xbfb8aa3b, v61
	v_exp_f32_e32 v69, v69
	v_mul_f32_e32 v64, v97, v64
	v_mul_f32_e32 v64, v64, v68
	v_add_f32_e32 v69, 1.0, v69
	v_div_scale_f32 v95, s[4:5], v69, v69, v61
	v_rcp_f32_e32 v96, v95
	s_nop 0
	v_fma_f32 v97, -v95, v96, 1.0
	v_fmac_f32_e32 v96, v97, v96
	v_div_scale_f32 v97, vcc, v61, v69, v61
	v_mul_f32_e32 v98, v97, v96
	v_fma_f32 v99, -v95, v98, v97
	v_fmac_f32_e32 v98, v99, v96
	v_fma_f32 v95, -v95, v98, v97
	v_div_fmas_f32 v95, v95, v96, v98
	v_div_fixup_f32 v61, v95, v69, v61
	v_mul_f32_e32 v61, v65, v61
	v_mul_f32_e32 v61, v61, v68
	v_cvt_pk_bf16_f32 v61, v64, v61
	v_lshlrev_b32_e32 v64, 16, v62
	v_mul_f32_e32 v65, 0xbfb8aa3b, v64
	v_exp_f32_e32 v65, v65
	v_and_b32_e32 v62, 0xffff0000, v62
	v_add_f32_e32 v65, 1.0, v65
	v_div_scale_f32 v69, s[4:5], v65, v65, v64
	v_rcp_f32_e32 v95, v69
	s_nop 0
	v_fma_f32 v96, -v69, v95, 1.0
	v_fmac_f32_e32 v95, v96, v95
	v_div_scale_f32 v96, vcc, v64, v65, v64
	v_mul_f32_e32 v97, v96, v95
	v_fma_f32 v98, -v69, v97, v96
	v_fmac_f32_e32 v97, v98, v95
	v_fma_f32 v69, -v69, v97, v96
	v_div_fmas_f32 v69, v69, v95, v97
	v_div_fixup_f32 v64, v69, v65, v64
	v_mul_f32_e32 v65, 0xbfb8aa3b, v62
	v_exp_f32_e32 v65, v65
	v_mul_f32_e32 v64, v67, v64
	v_mul_f32_e32 v64, v64, v68
	v_add_f32_e32 v65, 1.0, v65
	v_div_scale_f32 v67, s[4:5], v65, v65, v62
	v_rcp_f32_e32 v69, v67
	s_nop 0
	v_fma_f32 v95, -v67, v69, 1.0
	v_fmac_f32_e32 v69, v95, v69
	v_div_scale_f32 v95, vcc, v62, v65, v62
	v_mul_f32_e32 v96, v95, v69
	v_fma_f32 v97, -v67, v96, v95
	v_fmac_f32_e32 v96, v97, v69
	v_fma_f32 v67, -v67, v96, v95
	v_div_fmas_f32 v67, v67, v69, v96
	v_div_fixup_f32 v62, v67, v65, v62
	v_mul_f32_e32 v62, v71, v62
	v_mul_f32_e32 v62, v62, v68
	v_cvt_pk_bf16_f32 v62, v64, v62
	v_lshlrev_b32_e32 v64, 16, v63
	v_mul_f32_e32 v65, 0xbfb8aa3b, v64
	v_exp_f32_e32 v65, v65
	v_and_b32_e32 v63, 0xffff0000, v63
	v_add_f32_e32 v65, 1.0, v65
	v_div_scale_f32 v67, s[4:5], v65, v65, v64
	v_rcp_f32_e32 v69, v67
	s_nop 0
	v_fma_f32 v71, -v67, v69, 1.0
	v_fmac_f32_e32 v69, v71, v69
	v_div_scale_f32 v71, vcc, v64, v65, v64
	v_mul_f32_e32 v95, v71, v69
	v_fma_f32 v96, -v67, v95, v71
	v_fmac_f32_e32 v95, v96, v69
	v_fma_f32 v67, -v67, v95, v71
	v_div_fmas_f32 v67, v67, v69, v95
	v_div_fixup_f32 v64, v67, v65, v64
	v_mul_f32_e32 v65, 0xbfb8aa3b, v63
	v_exp_f32_e32 v65, v65
	v_mul_f32_e32 v64, v66, v64
	v_mul_f32_e32 v64, v64, v68
	v_add_f32_e32 v65, 1.0, v65
	v_div_scale_f32 v66, s[4:5], v65, v65, v63
	v_rcp_f32_e32 v67, v66
	s_nop 0
	v_fma_f32 v69, -v66, v67, 1.0
	v_fmac_f32_e32 v67, v69, v67
	v_div_scale_f32 v69, vcc, v63, v65, v63
	v_mul_f32_e32 v71, v69, v67
	v_fma_f32 v95, -v66, v71, v69
	v_fmac_f32_e32 v71, v95, v67
	v_fma_f32 v66, -v66, v71, v69
	v_div_fmas_f32 v66, v66, v67, v71
	v_div_fixup_f32 v63, v66, v65, v63
	v_mul_f32_e32 v63, v70, v63
	v_mul_f32_e32 v63, v63, v68
	v_cvt_pk_bf16_f32 v63, v64, v63
	v_lshlrev_b64 v[64:65], 13, v[92:93]
	v_lshl_add_u64 v[64:65], s[46:47], 0, v[64:65]
	v_lshl_add_u64 v[64:65], v[64:65], 0, v[174:175]
	v_lshl_add_u64 v[64:65], v[64:65], 0, v[74:75]
	global_store_dwordx4 v[64:65], v[60:63], off
	s_waitcnt vmcnt(15)
	v_lshlrev_b32_e32 v67, 16, v54
	v_lshlrev_b32_e32 v66, 16, v55
	s_waitcnt vmcnt(14)
	v_lshlrev_b32_e32 v60, 16, v56
	v_lshlrev_b32_e32 v62, 16, v52
	v_lshlrev_b32_e32 v61, 16, v57
	v_lshlrev_b32_e32 v63, 16, v53
	v_and_b32_e32 v56, 0xffff0000, v56
	v_and_b32_e32 v52, 0xffff0000, v52
	v_and_b32_e32 v57, 0xffff0000, v57
	v_and_b32_e32 v53, 0xffff0000, v53
	v_pk_add_f32 v[60:61], v[62:63], v[60:61]
	v_lshlrev_b32_e32 v63, 16, v58
	v_lshlrev_b32_e32 v62, 16, v59
	v_pk_add_f32 v[52:53], v[52:53], v[56:57]
	v_pk_mul_f32 v[56:57], v[60:61], v[60:61]
	v_and_b32_e32 v69, 0xffff0000, v58
	v_and_b32_e32 v71, 0xffff0000, v54
	v_and_b32_e32 v68, 0xffff0000, v59
	v_and_b32_e32 v70, 0xffff0000, v55
	v_pk_add_f32 v[54:55], v[66:67], v[62:63]
	v_pk_fma_f32 v[56:57], v[52:53], v[52:53], v[56:57]
	v_pk_add_f32 v[58:59], v[70:71], v[68:69]
	v_pk_mul_f32 v[62:63], v[54:55], v[54:55]
	v_add_f32_e32 v56, v56, v57
	v_pk_fma_f32 v[62:63], v[58:59], v[58:59], v[62:63]
	s_nop 0
	v_add_f32_e32 v56, v63, v56
	v_add_f32_e32 v56, v62, v56
	s_nop 1
	v_add_f32_dpp v56, v56, v56 row_ror:8 row_mask:0xf bank_mask:0xf bound_ctrl:1
	s_nop 1
	v_add_f32_dpp v56, v56, v56 row_ror:4 row_mask:0xf bank_mask:0xf bound_ctrl:1
	s_nop 1
	v_add_f32_dpp v56, v56, v56 row_ror:2 row_mask:0xf bank_mask:0xf bound_ctrl:1
	s_nop 1
	v_add_f32_dpp v56, v56, v56 row_ror:1 row_mask:0xf bank_mask:0xf bound_ctrl:1
	s_nop 0
	v_readlane_b32 s1, v56, 16
	v_readlane_b32 s2, v56, 48
	v_readlane_b32 s4, v56, 0
	v_readlane_b32 s5, v56, 32
	v_mov_b32_e32 v56, s1
	v_mov_b32_e32 v57, s2
	v_pk_add_f32 v[56:57], s[4:5], v[56:57]
	s_nop 0
	v_add_f32_e32 v56, v56, v57
	v_fmamk_f32 v56, v56, 0x3b000000, v173
	v_cmp_gt_f32_e32 vcc, s19, v56
	v_mul_f32_e32 v57, 0x4f800000, v56
	s_nop 0
	v_cndmask_b32_e32 v56, v56, v57, vcc
	v_sqrt_f32_e32 v57, v56
	s_nop 0
	v_add_u32_e32 v62, -1, v57
	v_fma_f32 v63, -v62, v57, v56
	v_cmp_ge_f32_e64 s[38:39], 0, v63
	v_add_u32_e32 v63, 1, v57
	s_nop 0
	v_cndmask_b32_e64 v62, v57, v62, s[38:39]
	v_fma_f32 v57, -v63, v57, v56
	v_cmp_lt_f32_e64 s[38:39], 0, v57
	s_nop 1
	v_cndmask_b32_e64 v57, v62, v63, s[38:39]
	v_mul_f32_e32 v62, 0x37800000, v57
	v_cndmask_b32_e32 v57, v57, v62, vcc
	v_cmp_class_f32_e32 vcc, v56, v244
	s_nop 1
	v_cndmask_b32_e32 v56, v57, v56, vcc
	v_div_scale_f32 v57, s[4:5], v56, v56, 1.0
	v_rcp_f32_e32 v62, v57
	s_nop 0
	v_fma_f32 v63, -v57, v62, 1.0
	v_fmac_f32_e32 v62, v63, v62
	v_div_scale_f32 v63, vcc, 1.0, v56, 1.0
	v_mul_f32_e32 v66, v63, v62
	v_fma_f32 v67, -v57, v66, v63
	v_fmac_f32_e32 v66, v67, v62
	v_fma_f32 v57, -v57, v66, v63
	v_div_fmas_f32 v57, v57, v62, v66
	v_div_fixup_f32 v56, v57, v56, 1.0
	s_waitcnt vmcnt(13)
	v_lshlrev_b32_e32 v57, 16, v48
	v_mul_f32_e32 v62, 0xbfb8aa3b, v57
	v_exp_f32_e32 v62, v62
	v_and_b32_e32 v48, 0xffff0000, v48
	v_add_f32_e32 v62, 1.0, v62
	v_div_scale_f32 v63, s[4:5], v62, v62, v57
	v_rcp_f32_e32 v66, v63
	s_nop 0
	v_fma_f32 v67, -v63, v66, 1.0
	v_fmac_f32_e32 v66, v67, v66
	v_div_scale_f32 v67, vcc, v57, v62, v57
	v_mul_f32_e32 v68, v67, v66
	v_fma_f32 v69, -v63, v68, v67
	v_fmac_f32_e32 v68, v69, v66
	v_fma_f32 v63, -v63, v68, v67
	v_div_fmas_f32 v63, v63, v66, v68
	v_div_fixup_f32 v57, v63, v62, v57
	v_mul_f32_e32 v57, v60, v57
	v_mul_f32_e32 v60, 0xbfb8aa3b, v48
	v_exp_f32_e32 v60, v60
	v_mul_f32_e32 v57, v57, v56
	v_add_f32_e32 v60, 1.0, v60
	v_div_scale_f32 v62, s[4:5], v60, v60, v48
	v_rcp_f32_e32 v63, v62
	s_nop 0
	v_fma_f32 v66, -v62, v63, 1.0
	v_fmac_f32_e32 v63, v66, v63
	v_div_scale_f32 v66, vcc, v48, v60, v48
	v_mul_f32_e32 v67, v66, v63
	v_fma_f32 v68, -v62, v67, v66
	v_fmac_f32_e32 v67, v68, v63
	v_fma_f32 v62, -v62, v67, v66
	v_div_fmas_f32 v62, v62, v63, v67
	v_div_fixup_f32 v48, v62, v60, v48
	v_mul_f32_e32 v48, v52, v48
	v_mul_f32_e32 v48, v48, v56
	v_lshlrev_b32_e32 v52, 16, v49
	v_cvt_pk_bf16_f32 v48, v57, v48
	v_mul_f32_e32 v57, 0xbfb8aa3b, v52
	v_exp_f32_e32 v57, v57
	v_and_b32_e32 v49, 0xffff0000, v49
	v_add_f32_e32 v57, 1.0, v57
	v_div_scale_f32 v60, s[4:5], v57, v57, v52
	v_rcp_f32_e32 v62, v60
	s_nop 0
	v_fma_f32 v63, -v60, v62, 1.0
	v_fmac_f32_e32 v62, v63, v62
	v_div_scale_f32 v63, vcc, v52, v57, v52
	v_mul_f32_e32 v66, v63, v62
	v_fma_f32 v67, -v60, v66, v63
	v_fmac_f32_e32 v66, v67, v62
	v_fma_f32 v60, -v60, v66, v63
	v_div_fmas_f32 v60, v60, v62, v66
	v_div_fixup_f32 v52, v60, v57, v52
	v_mul_f32_e32 v57, 0xbfb8aa3b, v49
	v_exp_f32_e32 v57, v57
	v_mul_f32_e32 v52, v61, v52
	v_mul_f32_e32 v52, v52, v56
	v_add_f32_e32 v57, 1.0, v57
	v_div_scale_f32 v60, s[4:5], v57, v57, v49
	v_rcp_f32_e32 v61, v60
	s_nop 0
	v_fma_f32 v62, -v60, v61, 1.0
	v_fmac_f32_e32 v61, v62, v61
	v_div_scale_f32 v62, vcc, v49, v57, v49
	v_mul_f32_e32 v63, v62, v61
	v_fma_f32 v66, -v60, v63, v62
	v_fmac_f32_e32 v63, v66, v61
	v_fma_f32 v60, -v60, v63, v62
	v_div_fmas_f32 v60, v60, v61, v63
	v_div_fixup_f32 v49, v60, v57, v49
	v_mul_f32_e32 v49, v53, v49
	v_mul_f32_e32 v49, v49, v56
	v_cvt_pk_bf16_f32 v49, v52, v49
	v_lshlrev_b32_e32 v52, 16, v50
	v_mul_f32_e32 v53, 0xbfb8aa3b, v52
	v_exp_f32_e32 v53, v53
	v_and_b32_e32 v50, 0xffff0000, v50
	v_add_f32_e32 v53, 1.0, v53
	v_div_scale_f32 v57, s[4:5], v53, v53, v52
	v_rcp_f32_e32 v60, v57
	s_nop 0
	v_fma_f32 v61, -v57, v60, 1.0
	v_fmac_f32_e32 v60, v61, v60
	v_div_scale_f32 v61, vcc, v52, v53, v52
	v_mul_f32_e32 v62, v61, v60
	v_fma_f32 v63, -v57, v62, v61
	v_fmac_f32_e32 v62, v63, v60
	v_fma_f32 v57, -v57, v62, v61
	v_div_fmas_f32 v57, v57, v60, v62
	v_div_fixup_f32 v52, v57, v53, v52
	v_mul_f32_e32 v53, 0xbfb8aa3b, v50
	v_exp_f32_e32 v53, v53
	v_mul_f32_e32 v52, v55, v52
	v_mul_f32_e32 v52, v52, v56
	v_add_f32_e32 v53, 1.0, v53
	v_div_scale_f32 v55, s[4:5], v53, v53, v50
	v_rcp_f32_e32 v57, v55
	s_nop 0
	v_fma_f32 v60, -v55, v57, 1.0
	v_fmac_f32_e32 v57, v60, v57
	v_div_scale_f32 v60, vcc, v50, v53, v50
	v_mul_f32_e32 v61, v60, v57
	v_fma_f32 v62, -v55, v61, v60
	v_fmac_f32_e32 v61, v62, v57
	v_fma_f32 v55, -v55, v61, v60
	v_div_fmas_f32 v55, v55, v57, v61
	v_div_fixup_f32 v50, v55, v53, v50
	v_mul_f32_e32 v50, v59, v50
	v_mul_f32_e32 v50, v50, v56
	v_cvt_pk_bf16_f32 v50, v52, v50
	v_lshlrev_b32_e32 v52, 16, v51
	v_mul_f32_e32 v53, 0xbfb8aa3b, v52
	v_exp_f32_e32 v53, v53
	v_and_b32_e32 v51, 0xffff0000, v51
	v_add_f32_e32 v53, 1.0, v53
	v_div_scale_f32 v55, s[4:5], v53, v53, v52
	v_rcp_f32_e32 v57, v55
	s_nop 0
	v_fma_f32 v59, -v55, v57, 1.0
	v_fmac_f32_e32 v57, v59, v57
	v_div_scale_f32 v59, vcc, v52, v53, v52
	v_mul_f32_e32 v60, v59, v57
	v_fma_f32 v61, -v55, v60, v59
	v_fmac_f32_e32 v60, v61, v57
	v_fma_f32 v55, -v55, v60, v59
	v_div_fmas_f32 v55, v55, v57, v60
	v_div_fixup_f32 v52, v55, v53, v52
	v_mul_f32_e32 v53, 0xbfb8aa3b, v51
	v_exp_f32_e32 v53, v53
	v_mul_f32_e32 v52, v54, v52
	v_mul_f32_e32 v52, v52, v56
	v_add_f32_e32 v53, 1.0, v53
	v_div_scale_f32 v54, s[4:5], v53, v53, v51
	v_rcp_f32_e32 v55, v54
	s_nop 0
	v_fma_f32 v57, -v54, v55, 1.0
	v_fmac_f32_e32 v55, v57, v55
	v_div_scale_f32 v57, vcc, v51, v53, v51
	v_mul_f32_e32 v59, v57, v55
	v_fma_f32 v60, -v54, v59, v57
	v_fmac_f32_e32 v59, v60, v55
	v_fma_f32 v54, -v54, v59, v57
	v_div_fmas_f32 v54, v54, v55, v59
	v_div_fixup_f32 v51, v54, v53, v51
	v_mul_f32_e32 v51, v58, v51
	v_mul_f32_e32 v51, v51, v56
	v_cvt_pk_bf16_f32 v51, v52, v51
	global_store_dwordx4 v[64:65], v[48:51], off offset:1024
	s_waitcnt vmcnt(13)
	v_lshlrev_b32_e32 v53, 16, v42
	v_lshlrev_b32_e32 v52, 16, v43
	s_waitcnt vmcnt(12)
	v_lshlrev_b32_e32 v48, 16, v44
	v_lshlrev_b32_e32 v50, 16, v40
	v_lshlrev_b32_e32 v49, 16, v45
	v_lshlrev_b32_e32 v51, 16, v41
	v_and_b32_e32 v44, 0xffff0000, v44
	v_and_b32_e32 v40, 0xffff0000, v40
	v_and_b32_e32 v45, 0xffff0000, v45
	v_and_b32_e32 v41, 0xffff0000, v41
	v_pk_add_f32 v[48:49], v[50:51], v[48:49]
	v_lshlrev_b32_e32 v51, 16, v46
	v_lshlrev_b32_e32 v50, 16, v47
	v_pk_add_f32 v[40:41], v[40:41], v[44:45]
	v_pk_mul_f32 v[44:45], v[48:49], v[48:49]
	v_and_b32_e32 v55, 0xffff0000, v46
	v_and_b32_e32 v57, 0xffff0000, v42
	v_and_b32_e32 v54, 0xffff0000, v47
	v_and_b32_e32 v56, 0xffff0000, v43
	v_pk_add_f32 v[42:43], v[52:53], v[50:51]
	v_pk_fma_f32 v[44:45], v[40:41], v[40:41], v[44:45]
	v_pk_add_f32 v[46:47], v[56:57], v[54:55]
	v_pk_mul_f32 v[50:51], v[42:43], v[42:43]
	v_add_f32_e32 v44, v44, v45
	v_pk_fma_f32 v[50:51], v[46:47], v[46:47], v[50:51]
	s_nop 0
	v_add_f32_e32 v44, v51, v44
	v_add_f32_e32 v44, v50, v44
	s_nop 1
	v_add_f32_dpp v44, v44, v44 row_ror:8 row_mask:0xf bank_mask:0xf bound_ctrl:1
	s_nop 1
	v_add_f32_dpp v44, v44, v44 row_ror:4 row_mask:0xf bank_mask:0xf bound_ctrl:1
	s_nop 1
	v_add_f32_dpp v44, v44, v44 row_ror:2 row_mask:0xf bank_mask:0xf bound_ctrl:1
	s_nop 1
	v_add_f32_dpp v44, v44, v44 row_ror:1 row_mask:0xf bank_mask:0xf bound_ctrl:1
	s_nop 0
	v_readlane_b32 s1, v44, 16
	v_readlane_b32 s2, v44, 48
	v_readlane_b32 s4, v44, 0
	v_readlane_b32 s5, v44, 32
	v_mov_b32_e32 v44, s1
	v_mov_b32_e32 v45, s2
	v_pk_add_f32 v[44:45], s[4:5], v[44:45]
	s_nop 0
	v_add_f32_e32 v44, v44, v45
	v_fmamk_f32 v44, v44, 0x3b000000, v173
	v_cmp_gt_f32_e32 vcc, s19, v44
	v_mul_f32_e32 v45, 0x4f800000, v44
	s_nop 0
	v_cndmask_b32_e32 v44, v44, v45, vcc
	v_sqrt_f32_e32 v45, v44
	s_nop 0
	v_add_u32_e32 v50, -1, v45
	v_fma_f32 v51, -v50, v45, v44
	v_cmp_ge_f32_e64 s[38:39], 0, v51
	v_add_u32_e32 v51, 1, v45
	s_nop 0
	v_cndmask_b32_e64 v50, v45, v50, s[38:39]
	v_fma_f32 v45, -v51, v45, v44
	v_cmp_lt_f32_e64 s[38:39], 0, v45
	s_nop 1
	v_cndmask_b32_e64 v45, v50, v51, s[38:39]
	v_mul_f32_e32 v50, 0x37800000, v45
	v_cndmask_b32_e32 v45, v45, v50, vcc
	v_cmp_class_f32_e32 vcc, v44, v244
	s_nop 1
	v_cndmask_b32_e32 v44, v45, v44, vcc
	v_div_scale_f32 v45, s[4:5], v44, v44, 1.0
	v_rcp_f32_e32 v50, v45
	s_nop 0
	v_fma_f32 v51, -v45, v50, 1.0
	v_fmac_f32_e32 v50, v51, v50
	v_div_scale_f32 v51, vcc, 1.0, v44, 1.0
	v_mul_f32_e32 v52, v51, v50
	v_fma_f32 v53, -v45, v52, v51
	v_fmac_f32_e32 v52, v53, v50
	v_fma_f32 v45, -v45, v52, v51
	v_div_fmas_f32 v45, v45, v50, v52
	v_div_fixup_f32 v44, v45, v44, 1.0
	s_waitcnt vmcnt(11)
	v_lshlrev_b32_e32 v45, 16, v36
	v_mul_f32_e32 v50, 0xbfb8aa3b, v45
	v_exp_f32_e32 v50, v50
	v_and_b32_e32 v36, 0xffff0000, v36
	v_add_f32_e32 v50, 1.0, v50
	v_div_scale_f32 v51, s[4:5], v50, v50, v45
	v_rcp_f32_e32 v52, v51
	s_nop 0
	v_fma_f32 v53, -v51, v52, 1.0
	v_fmac_f32_e32 v52, v53, v52
	v_div_scale_f32 v53, vcc, v45, v50, v45
	v_mul_f32_e32 v54, v53, v52
	v_fma_f32 v55, -v51, v54, v53
	v_fmac_f32_e32 v54, v55, v52
	v_fma_f32 v51, -v51, v54, v53
	v_div_fmas_f32 v51, v51, v52, v54
	v_div_fixup_f32 v45, v51, v50, v45
	v_mul_f32_e32 v45, v48, v45
	v_mul_f32_e32 v48, 0xbfb8aa3b, v36
	v_exp_f32_e32 v48, v48
	v_mul_f32_e32 v45, v45, v44
	v_add_f32_e32 v48, 1.0, v48
	v_div_scale_f32 v50, s[4:5], v48, v48, v36
	v_rcp_f32_e32 v51, v50
	s_nop 0
	v_fma_f32 v52, -v50, v51, 1.0
	v_fmac_f32_e32 v51, v52, v51
	v_div_scale_f32 v52, vcc, v36, v48, v36
	v_mul_f32_e32 v53, v52, v51
	v_fma_f32 v54, -v50, v53, v52
	v_fmac_f32_e32 v53, v54, v51
	v_fma_f32 v50, -v50, v53, v52
	v_div_fmas_f32 v50, v50, v51, v53
	v_div_fixup_f32 v36, v50, v48, v36
	v_mul_f32_e32 v36, v40, v36
	v_mul_f32_e32 v36, v36, v44
	v_lshlrev_b32_e32 v40, 16, v37
	v_cvt_pk_bf16_f32 v36, v45, v36
	v_mul_f32_e32 v45, 0xbfb8aa3b, v40
	v_exp_f32_e32 v45, v45
	v_and_b32_e32 v37, 0xffff0000, v37
	v_add_f32_e32 v45, 1.0, v45
	v_div_scale_f32 v48, s[4:5], v45, v45, v40
	v_rcp_f32_e32 v50, v48
	s_nop 0
	v_fma_f32 v51, -v48, v50, 1.0
	v_fmac_f32_e32 v50, v51, v50
	v_div_scale_f32 v51, vcc, v40, v45, v40
	v_mul_f32_e32 v52, v51, v50
	v_fma_f32 v53, -v48, v52, v51
	v_fmac_f32_e32 v52, v53, v50
	v_fma_f32 v48, -v48, v52, v51
	v_div_fmas_f32 v48, v48, v50, v52
	v_div_fixup_f32 v40, v48, v45, v40
	v_mul_f32_e32 v45, 0xbfb8aa3b, v37
	v_exp_f32_e32 v45, v45
	v_mul_f32_e32 v40, v49, v40
	v_mul_f32_e32 v40, v40, v44
	v_add_f32_e32 v45, 1.0, v45
	v_div_scale_f32 v48, s[4:5], v45, v45, v37
	v_rcp_f32_e32 v49, v48
	s_nop 0
	v_fma_f32 v50, -v48, v49, 1.0
	v_fmac_f32_e32 v49, v50, v49
	v_div_scale_f32 v50, vcc, v37, v45, v37
	v_mul_f32_e32 v51, v50, v49
	v_fma_f32 v52, -v48, v51, v50
	v_fmac_f32_e32 v51, v52, v49
	v_fma_f32 v48, -v48, v51, v50
	v_div_fmas_f32 v48, v48, v49, v51
	v_div_fixup_f32 v37, v48, v45, v37
	v_mul_f32_e32 v37, v41, v37
	v_mul_f32_e32 v37, v37, v44
	v_cvt_pk_bf16_f32 v37, v40, v37
	v_lshlrev_b32_e32 v40, 16, v38
	v_mul_f32_e32 v41, 0xbfb8aa3b, v40
	v_exp_f32_e32 v41, v41
	v_and_b32_e32 v38, 0xffff0000, v38
	v_add_f32_e32 v41, 1.0, v41
	v_div_scale_f32 v45, s[4:5], v41, v41, v40
	v_rcp_f32_e32 v48, v45
	s_nop 0
	v_fma_f32 v49, -v45, v48, 1.0
	v_fmac_f32_e32 v48, v49, v48
	v_div_scale_f32 v49, vcc, v40, v41, v40
	v_mul_f32_e32 v50, v49, v48
	v_fma_f32 v51, -v45, v50, v49
	v_fmac_f32_e32 v50, v51, v48
	v_fma_f32 v45, -v45, v50, v49
	v_div_fmas_f32 v45, v45, v48, v50
	v_div_fixup_f32 v40, v45, v41, v40
	v_mul_f32_e32 v41, 0xbfb8aa3b, v38
	v_exp_f32_e32 v41, v41
	v_mul_f32_e32 v40, v43, v40
	v_mul_f32_e32 v40, v40, v44
	v_add_f32_e32 v41, 1.0, v41
	v_div_scale_f32 v43, s[4:5], v41, v41, v38
	v_rcp_f32_e32 v45, v43
	s_nop 0
	v_fma_f32 v48, -v43, v45, 1.0
	v_fmac_f32_e32 v45, v48, v45
	v_div_scale_f32 v48, vcc, v38, v41, v38
	v_mul_f32_e32 v49, v48, v45
	v_fma_f32 v50, -v43, v49, v48
	v_fmac_f32_e32 v49, v50, v45
	v_fma_f32 v43, -v43, v49, v48
	v_div_fmas_f32 v43, v43, v45, v49
	v_div_fixup_f32 v38, v43, v41, v38
	v_mul_f32_e32 v38, v47, v38
	v_mul_f32_e32 v38, v38, v44
	v_cvt_pk_bf16_f32 v38, v40, v38
	v_lshlrev_b32_e32 v40, 16, v39
	v_mul_f32_e32 v41, 0xbfb8aa3b, v40
	v_exp_f32_e32 v41, v41
	v_and_b32_e32 v39, 0xffff0000, v39
	v_add_f32_e32 v41, 1.0, v41
	v_div_scale_f32 v43, s[4:5], v41, v41, v40
	v_rcp_f32_e32 v45, v43
	s_nop 0
	v_fma_f32 v47, -v43, v45, 1.0
	v_fmac_f32_e32 v45, v47, v45
	v_div_scale_f32 v47, vcc, v40, v41, v40
	v_mul_f32_e32 v48, v47, v45
	v_fma_f32 v49, -v43, v48, v47
	v_fmac_f32_e32 v48, v49, v45
	v_fma_f32 v43, -v43, v48, v47
	v_div_fmas_f32 v43, v43, v45, v48
	v_div_fixup_f32 v40, v43, v41, v40
	v_mul_f32_e32 v41, 0xbfb8aa3b, v39
	v_exp_f32_e32 v41, v41
	v_mul_f32_e32 v40, v42, v40
	v_mul_f32_e32 v40, v40, v44
	v_add_f32_e32 v41, 1.0, v41
	v_div_scale_f32 v42, s[4:5], v41, v41, v39
	v_rcp_f32_e32 v43, v42
	s_nop 0
	v_fma_f32 v45, -v42, v43, 1.0
	v_fmac_f32_e32 v43, v45, v43
	v_div_scale_f32 v45, vcc, v39, v41, v39
	v_mul_f32_e32 v47, v45, v43
	v_fma_f32 v48, -v42, v47, v45
	v_fmac_f32_e32 v47, v48, v43
	v_fma_f32 v42, -v42, v47, v45
	v_div_fmas_f32 v42, v42, v43, v47
	v_div_fixup_f32 v39, v42, v41, v39
	v_mul_f32_e32 v39, v46, v39
	v_mul_f32_e32 v39, v39, v44
	v_cvt_pk_bf16_f32 v39, v40, v39
	v_lshlrev_b64 v[40:41], 13, v[88:89]
	v_lshl_add_u64 v[40:41], s[46:47], 0, v[40:41]
	v_lshl_add_u64 v[40:41], v[40:41], 0, v[90:91]
	v_lshl_add_u64 v[40:41], v[40:41], 0, v[74:75]
	global_store_dwordx4 v[40:41], v[36:39], off
	s_waitcnt vmcnt(11)
	v_lshlrev_b32_e32 v41, 16, v30
	v_lshlrev_b32_e32 v40, 16, v31
	s_waitcnt vmcnt(10)
	v_lshlrev_b32_e32 v36, 16, v32
	v_lshlrev_b32_e32 v38, 16, v28
	v_lshlrev_b32_e32 v37, 16, v33
	v_lshlrev_b32_e32 v39, 16, v29
	v_and_b32_e32 v32, 0xffff0000, v32
	v_and_b32_e32 v28, 0xffff0000, v28
	v_and_b32_e32 v33, 0xffff0000, v33
	v_and_b32_e32 v29, 0xffff0000, v29
	v_pk_add_f32 v[36:37], v[38:39], v[36:37]
	v_lshlrev_b32_e32 v39, 16, v34
	v_lshlrev_b32_e32 v38, 16, v35
	v_pk_add_f32 v[28:29], v[28:29], v[32:33]
	v_pk_mul_f32 v[32:33], v[36:37], v[36:37]
	v_and_b32_e32 v43, 0xffff0000, v34
	v_and_b32_e32 v45, 0xffff0000, v30
	v_and_b32_e32 v42, 0xffff0000, v35
	v_and_b32_e32 v44, 0xffff0000, v31
	v_pk_add_f32 v[30:31], v[40:41], v[38:39]
	v_pk_fma_f32 v[32:33], v[28:29], v[28:29], v[32:33]
	v_pk_add_f32 v[34:35], v[44:45], v[42:43]
	v_pk_mul_f32 v[38:39], v[30:31], v[30:31]
	v_add_f32_e32 v32, v32, v33
	v_pk_fma_f32 v[38:39], v[34:35], v[34:35], v[38:39]
	s_nop 0
	v_add_f32_e32 v32, v39, v32
	v_add_f32_e32 v32, v38, v32
	s_nop 1
	v_add_f32_dpp v32, v32, v32 row_ror:8 row_mask:0xf bank_mask:0xf bound_ctrl:1
	s_nop 1
	v_add_f32_dpp v32, v32, v32 row_ror:4 row_mask:0xf bank_mask:0xf bound_ctrl:1
	s_nop 1
	v_add_f32_dpp v32, v32, v32 row_ror:2 row_mask:0xf bank_mask:0xf bound_ctrl:1
	s_nop 1
	v_add_f32_dpp v32, v32, v32 row_ror:1 row_mask:0xf bank_mask:0xf bound_ctrl:1
	s_nop 0
	v_readlane_b32 s1, v32, 16
	v_readlane_b32 s2, v32, 48
	v_readlane_b32 s4, v32, 0
	v_readlane_b32 s5, v32, 32
	v_mov_b32_e32 v32, s1
	v_mov_b32_e32 v33, s2
	v_pk_add_f32 v[32:33], s[4:5], v[32:33]
	s_nop 0
	v_add_f32_e32 v32, v32, v33
	v_fmamk_f32 v32, v32, 0x3b000000, v173
	v_cmp_gt_f32_e32 vcc, s19, v32
	v_mul_f32_e32 v33, 0x4f800000, v32
	s_nop 0
	v_cndmask_b32_e32 v32, v32, v33, vcc
	v_sqrt_f32_e32 v33, v32
	s_nop 0
	v_add_u32_e32 v38, -1, v33
	v_fma_f32 v39, -v38, v33, v32
	v_cmp_ge_f32_e64 s[38:39], 0, v39
	v_add_u32_e32 v39, 1, v33
	s_nop 0
	v_cndmask_b32_e64 v38, v33, v38, s[38:39]
	v_fma_f32 v33, -v39, v33, v32
	v_cmp_lt_f32_e64 s[38:39], 0, v33
	s_nop 1
	v_cndmask_b32_e64 v33, v38, v39, s[38:39]
	v_mul_f32_e32 v38, 0x37800000, v33
	v_cndmask_b32_e32 v33, v33, v38, vcc
	v_cmp_class_f32_e32 vcc, v32, v244
	s_nop 1
	v_cndmask_b32_e32 v32, v33, v32, vcc
	v_div_scale_f32 v33, s[4:5], v32, v32, 1.0
	v_rcp_f32_e32 v38, v33
	s_nop 0
	v_fma_f32 v39, -v33, v38, 1.0
	v_fmac_f32_e32 v38, v39, v38
	v_div_scale_f32 v39, vcc, 1.0, v32, 1.0
	v_mul_f32_e32 v40, v39, v38
	v_fma_f32 v41, -v33, v40, v39
	v_fmac_f32_e32 v40, v41, v38
	v_fma_f32 v33, -v33, v40, v39
	v_div_fmas_f32 v33, v33, v38, v40
	v_div_fixup_f32 v32, v33, v32, 1.0
	s_waitcnt vmcnt(9)
	v_lshlrev_b32_e32 v33, 16, v24
	v_mul_f32_e32 v38, 0xbfb8aa3b, v33
	v_exp_f32_e32 v38, v38
	v_and_b32_e32 v24, 0xffff0000, v24
	v_add_f32_e32 v38, 1.0, v38
	v_div_scale_f32 v39, s[4:5], v38, v38, v33
	v_rcp_f32_e32 v40, v39
	s_nop 0
	v_fma_f32 v41, -v39, v40, 1.0
	v_fmac_f32_e32 v40, v41, v40
	v_div_scale_f32 v41, vcc, v33, v38, v33
	v_mul_f32_e32 v42, v41, v40
	v_fma_f32 v43, -v39, v42, v41
	v_fmac_f32_e32 v42, v43, v40
	v_fma_f32 v39, -v39, v42, v41
	v_div_fmas_f32 v39, v39, v40, v42
	v_div_fixup_f32 v33, v39, v38, v33
	v_mul_f32_e32 v33, v36, v33
	v_mul_f32_e32 v36, 0xbfb8aa3b, v24
	v_exp_f32_e32 v36, v36
	v_mul_f32_e32 v33, v33, v32
	v_add_f32_e32 v36, 1.0, v36
	v_div_scale_f32 v38, s[4:5], v36, v36, v24
	v_rcp_f32_e32 v39, v38
	s_nop 0
	v_fma_f32 v40, -v38, v39, 1.0
	v_fmac_f32_e32 v39, v40, v39
	v_div_scale_f32 v40, vcc, v24, v36, v24
	v_mul_f32_e32 v41, v40, v39
	v_fma_f32 v42, -v38, v41, v40
	v_fmac_f32_e32 v41, v42, v39
	v_fma_f32 v38, -v38, v41, v40
	v_div_fmas_f32 v38, v38, v39, v41
	v_div_fixup_f32 v24, v38, v36, v24
	v_mul_f32_e32 v24, v28, v24
	v_mul_f32_e32 v24, v24, v32
	v_lshlrev_b32_e32 v28, 16, v25
	v_cvt_pk_bf16_f32 v24, v33, v24
	v_mul_f32_e32 v33, 0xbfb8aa3b, v28
	v_exp_f32_e32 v33, v33
	v_and_b32_e32 v25, 0xffff0000, v25
	v_add_f32_e32 v33, 1.0, v33
	v_div_scale_f32 v36, s[4:5], v33, v33, v28
	v_rcp_f32_e32 v38, v36
	s_nop 0
	v_fma_f32 v39, -v36, v38, 1.0
	v_fmac_f32_e32 v38, v39, v38
	v_div_scale_f32 v39, vcc, v28, v33, v28
	v_mul_f32_e32 v40, v39, v38
	v_fma_f32 v41, -v36, v40, v39
	v_fmac_f32_e32 v40, v41, v38
	v_fma_f32 v36, -v36, v40, v39
	v_div_fmas_f32 v36, v36, v38, v40
	v_div_fixup_f32 v28, v36, v33, v28
	v_mul_f32_e32 v33, 0xbfb8aa3b, v25
	v_exp_f32_e32 v33, v33
	v_mul_f32_e32 v28, v37, v28
	v_mul_f32_e32 v28, v28, v32
	v_add_f32_e32 v33, 1.0, v33
	v_div_scale_f32 v36, s[4:5], v33, v33, v25
	v_rcp_f32_e32 v37, v36
	s_nop 0
	v_fma_f32 v38, -v36, v37, 1.0
	v_fmac_f32_e32 v37, v38, v37
	v_div_scale_f32 v38, vcc, v25, v33, v25
	v_mul_f32_e32 v39, v38, v37
	v_fma_f32 v40, -v36, v39, v38
	v_fmac_f32_e32 v39, v40, v37
	v_fma_f32 v36, -v36, v39, v38
	v_div_fmas_f32 v36, v36, v37, v39
	v_div_fixup_f32 v25, v36, v33, v25
	v_mul_f32_e32 v25, v29, v25
	v_mul_f32_e32 v25, v25, v32
	v_cvt_pk_bf16_f32 v25, v28, v25
	v_lshlrev_b32_e32 v28, 16, v26
	v_mul_f32_e32 v29, 0xbfb8aa3b, v28
	v_exp_f32_e32 v29, v29
	v_and_b32_e32 v26, 0xffff0000, v26
	v_add_f32_e32 v29, 1.0, v29
	v_div_scale_f32 v33, s[4:5], v29, v29, v28
	v_rcp_f32_e32 v36, v33
	s_nop 0
	v_fma_f32 v37, -v33, v36, 1.0
	v_fmac_f32_e32 v36, v37, v36
	v_div_scale_f32 v37, vcc, v28, v29, v28
	v_mul_f32_e32 v38, v37, v36
	v_fma_f32 v39, -v33, v38, v37
	v_fmac_f32_e32 v38, v39, v36
	v_fma_f32 v33, -v33, v38, v37
	v_div_fmas_f32 v33, v33, v36, v38
	v_div_fixup_f32 v28, v33, v29, v28
	v_mul_f32_e32 v29, 0xbfb8aa3b, v26
	v_exp_f32_e32 v29, v29
	v_mul_f32_e32 v28, v31, v28
	v_mul_f32_e32 v28, v28, v32
	v_add_f32_e32 v29, 1.0, v29
	v_div_scale_f32 v31, s[4:5], v29, v29, v26
	v_rcp_f32_e32 v33, v31
	s_nop 0
	v_fma_f32 v36, -v31, v33, 1.0
	v_fmac_f32_e32 v33, v36, v33
	v_div_scale_f32 v36, vcc, v26, v29, v26
	v_mul_f32_e32 v37, v36, v33
	v_fma_f32 v38, -v31, v37, v36
	v_fmac_f32_e32 v37, v38, v33
	v_fma_f32 v31, -v31, v37, v36
	v_div_fmas_f32 v31, v31, v33, v37
	v_div_fixup_f32 v26, v31, v29, v26
	v_mul_f32_e32 v26, v35, v26
	v_mul_f32_e32 v26, v26, v32
	v_cvt_pk_bf16_f32 v26, v28, v26
	v_lshlrev_b32_e32 v28, 16, v27
	v_mul_f32_e32 v29, 0xbfb8aa3b, v28
	v_exp_f32_e32 v29, v29
	v_and_b32_e32 v27, 0xffff0000, v27
	v_add_f32_e32 v29, 1.0, v29
	v_div_scale_f32 v31, s[4:5], v29, v29, v28
	v_rcp_f32_e32 v33, v31
	s_nop 0
	v_fma_f32 v35, -v31, v33, 1.0
	v_fmac_f32_e32 v33, v35, v33
	v_div_scale_f32 v35, vcc, v28, v29, v28
	v_mul_f32_e32 v36, v35, v33
	v_fma_f32 v37, -v31, v36, v35
	v_fmac_f32_e32 v36, v37, v33
	v_fma_f32 v31, -v31, v36, v35
	v_div_fmas_f32 v31, v31, v33, v36
	v_div_fixup_f32 v28, v31, v29, v28
	v_mul_f32_e32 v29, 0xbfb8aa3b, v27
	v_exp_f32_e32 v29, v29
	v_mul_f32_e32 v28, v30, v28
	v_mul_f32_e32 v28, v28, v32
	v_add_f32_e32 v29, 1.0, v29
	v_div_scale_f32 v30, s[4:5], v29, v29, v27
	v_rcp_f32_e32 v31, v30
	s_nop 0
	v_fma_f32 v33, -v30, v31, 1.0
	v_fmac_f32_e32 v31, v33, v31
	v_div_scale_f32 v33, vcc, v27, v29, v27
	v_mul_f32_e32 v35, v33, v31
	v_fma_f32 v36, -v30, v35, v33
	v_fmac_f32_e32 v35, v36, v31
	v_fma_f32 v30, -v30, v35, v33
	v_div_fmas_f32 v30, v30, v31, v35
	v_div_fixup_f32 v27, v30, v29, v27
	v_mul_f32_e32 v27, v34, v27
	v_mul_f32_e32 v27, v27, v32
	v_cvt_pk_bf16_f32 v27, v28, v27
	v_lshlrev_b64 v[28:29], 13, v[84:85]
	v_lshl_add_u64 v[28:29], s[46:47], 0, v[28:29]
	v_lshl_add_u64 v[28:29], v[28:29], 0, v[86:87]
	v_lshl_add_u64 v[28:29], v[28:29], 0, v[74:75]
	global_store_dwordx4 v[28:29], v[24:27], off
	s_waitcnt vmcnt(9)
	v_lshlrev_b32_e32 v29, 16, v18
	v_lshlrev_b32_e32 v28, 16, v19
	s_waitcnt vmcnt(8)
	v_lshlrev_b32_e32 v24, 16, v20
	v_lshlrev_b32_e32 v26, 16, v16
	v_lshlrev_b32_e32 v25, 16, v21
	v_lshlrev_b32_e32 v27, 16, v17
	v_and_b32_e32 v20, 0xffff0000, v20
	v_and_b32_e32 v16, 0xffff0000, v16
	v_and_b32_e32 v21, 0xffff0000, v21
	v_and_b32_e32 v17, 0xffff0000, v17
	v_pk_add_f32 v[24:25], v[26:27], v[24:25]
	v_lshlrev_b32_e32 v27, 16, v22
	v_lshlrev_b32_e32 v26, 16, v23
	v_pk_add_f32 v[16:17], v[16:17], v[20:21]
	v_pk_mul_f32 v[20:21], v[24:25], v[24:25]
	v_and_b32_e32 v31, 0xffff0000, v22
	v_and_b32_e32 v33, 0xffff0000, v18
	v_and_b32_e32 v30, 0xffff0000, v23
	v_and_b32_e32 v32, 0xffff0000, v19
	v_pk_add_f32 v[18:19], v[28:29], v[26:27]
	v_pk_fma_f32 v[20:21], v[16:17], v[16:17], v[20:21]
	v_pk_add_f32 v[22:23], v[32:33], v[30:31]
	v_pk_mul_f32 v[26:27], v[18:19], v[18:19]
	v_add_f32_e32 v20, v20, v21
	v_pk_fma_f32 v[26:27], v[22:23], v[22:23], v[26:27]
	s_nop 0
	v_add_f32_e32 v20, v27, v20
	v_add_f32_e32 v20, v26, v20
	s_nop 1
	v_add_f32_dpp v20, v20, v20 row_ror:8 row_mask:0xf bank_mask:0xf bound_ctrl:1
	s_nop 1
	v_add_f32_dpp v20, v20, v20 row_ror:4 row_mask:0xf bank_mask:0xf bound_ctrl:1
	s_nop 1
	v_add_f32_dpp v20, v20, v20 row_ror:2 row_mask:0xf bank_mask:0xf bound_ctrl:1
	s_nop 1
	v_add_f32_dpp v20, v20, v20 row_ror:1 row_mask:0xf bank_mask:0xf bound_ctrl:1
	s_nop 0
	v_readlane_b32 s1, v20, 16
	v_readlane_b32 s2, v20, 48
	v_readlane_b32 s4, v20, 0
	v_readlane_b32 s5, v20, 32
	v_mov_b32_e32 v20, s1
	v_mov_b32_e32 v21, s2
	v_pk_add_f32 v[20:21], s[4:5], v[20:21]
	s_nop 0
	v_add_f32_e32 v20, v20, v21
	v_fmamk_f32 v20, v20, 0x3b000000, v173
	v_cmp_gt_f32_e32 vcc, s19, v20
	v_mul_f32_e32 v21, 0x4f800000, v20
	s_nop 0
	v_cndmask_b32_e32 v20, v20, v21, vcc
	v_sqrt_f32_e32 v21, v20
	s_nop 0
	v_add_u32_e32 v26, -1, v21
	v_fma_f32 v27, -v26, v21, v20
	v_cmp_ge_f32_e64 s[38:39], 0, v27
	v_add_u32_e32 v27, 1, v21
	s_nop 0
	v_cndmask_b32_e64 v26, v21, v26, s[38:39]
	v_fma_f32 v21, -v27, v21, v20
	v_cmp_lt_f32_e64 s[38:39], 0, v21
	s_nop 1
	v_cndmask_b32_e64 v21, v26, v27, s[38:39]
	v_mul_f32_e32 v26, 0x37800000, v21
	v_cndmask_b32_e32 v21, v21, v26, vcc
	v_cmp_class_f32_e32 vcc, v20, v244
	s_nop 1
	v_cndmask_b32_e32 v20, v21, v20, vcc
	v_div_scale_f32 v21, s[4:5], v20, v20, 1.0
	v_rcp_f32_e32 v26, v21
	s_nop 0
	v_fma_f32 v27, -v21, v26, 1.0
	v_fmac_f32_e32 v26, v27, v26
	v_div_scale_f32 v27, vcc, 1.0, v20, 1.0
	v_mul_f32_e32 v28, v27, v26
	v_fma_f32 v29, -v21, v28, v27
	v_fmac_f32_e32 v28, v29, v26
	v_fma_f32 v21, -v21, v28, v27
	v_div_fmas_f32 v21, v21, v26, v28
	v_div_fixup_f32 v20, v21, v20, 1.0
	s_waitcnt vmcnt(7)
	v_lshlrev_b32_e32 v21, 16, v12
	v_mul_f32_e32 v26, 0xbfb8aa3b, v21
	v_exp_f32_e32 v26, v26
	v_and_b32_e32 v12, 0xffff0000, v12
	v_add_f32_e32 v26, 1.0, v26
	v_div_scale_f32 v27, s[4:5], v26, v26, v21
	v_rcp_f32_e32 v28, v27
	s_nop 0
	v_fma_f32 v29, -v27, v28, 1.0
	v_fmac_f32_e32 v28, v29, v28
	v_div_scale_f32 v29, vcc, v21, v26, v21
	v_mul_f32_e32 v30, v29, v28
	v_fma_f32 v31, -v27, v30, v29
	v_fmac_f32_e32 v30, v31, v28
	v_fma_f32 v27, -v27, v30, v29
	v_div_fmas_f32 v27, v27, v28, v30
	v_div_fixup_f32 v21, v27, v26, v21
	v_mul_f32_e32 v21, v24, v21
	v_mul_f32_e32 v24, 0xbfb8aa3b, v12
	v_exp_f32_e32 v24, v24
	v_mul_f32_e32 v21, v21, v20
	v_add_f32_e32 v24, 1.0, v24
	v_div_scale_f32 v26, s[4:5], v24, v24, v12
	v_rcp_f32_e32 v27, v26
	s_nop 0
	v_fma_f32 v28, -v26, v27, 1.0
	v_fmac_f32_e32 v27, v28, v27
	v_div_scale_f32 v28, vcc, v12, v24, v12
	v_mul_f32_e32 v29, v28, v27
	v_fma_f32 v30, -v26, v29, v28
	v_fmac_f32_e32 v29, v30, v27
	v_fma_f32 v26, -v26, v29, v28
	v_div_fmas_f32 v26, v26, v27, v29
	v_div_fixup_f32 v12, v26, v24, v12
	v_mul_f32_e32 v12, v16, v12
	v_mul_f32_e32 v12, v12, v20
	v_lshlrev_b32_e32 v16, 16, v13
	v_cvt_pk_bf16_f32 v12, v21, v12
	v_mul_f32_e32 v21, 0xbfb8aa3b, v16
	v_exp_f32_e32 v21, v21
	v_and_b32_e32 v13, 0xffff0000, v13
	v_add_f32_e32 v21, 1.0, v21
	v_div_scale_f32 v24, s[4:5], v21, v21, v16
	v_rcp_f32_e32 v26, v24
	s_nop 0
	v_fma_f32 v27, -v24, v26, 1.0
	v_fmac_f32_e32 v26, v27, v26
	v_div_scale_f32 v27, vcc, v16, v21, v16
	v_mul_f32_e32 v28, v27, v26
	v_fma_f32 v29, -v24, v28, v27
	v_fmac_f32_e32 v28, v29, v26
	v_fma_f32 v24, -v24, v28, v27
	v_div_fmas_f32 v24, v24, v26, v28
	v_div_fixup_f32 v16, v24, v21, v16
	v_mul_f32_e32 v21, 0xbfb8aa3b, v13
	v_exp_f32_e32 v21, v21
	v_mul_f32_e32 v16, v25, v16
	v_mul_f32_e32 v16, v16, v20
	v_add_f32_e32 v21, 1.0, v21
	v_div_scale_f32 v24, s[4:5], v21, v21, v13
	v_rcp_f32_e32 v25, v24
	s_nop 0
	v_fma_f32 v26, -v24, v25, 1.0
	v_fmac_f32_e32 v25, v26, v25
	v_div_scale_f32 v26, vcc, v13, v21, v13
	v_mul_f32_e32 v27, v26, v25
	v_fma_f32 v28, -v24, v27, v26
	v_fmac_f32_e32 v27, v28, v25
	v_fma_f32 v24, -v24, v27, v26
	v_div_fmas_f32 v24, v24, v25, v27
	v_div_fixup_f32 v13, v24, v21, v13
	v_mul_f32_e32 v13, v17, v13
	v_mul_f32_e32 v13, v13, v20
	v_cvt_pk_bf16_f32 v13, v16, v13
	v_lshlrev_b32_e32 v16, 16, v14
	v_mul_f32_e32 v17, 0xbfb8aa3b, v16
	v_exp_f32_e32 v17, v17
	v_and_b32_e32 v14, 0xffff0000, v14
	v_add_f32_e32 v17, 1.0, v17
	v_div_scale_f32 v21, s[4:5], v17, v17, v16
	v_rcp_f32_e32 v24, v21
	s_nop 0
	v_fma_f32 v25, -v21, v24, 1.0
	v_fmac_f32_e32 v24, v25, v24
	v_div_scale_f32 v25, vcc, v16, v17, v16
	v_mul_f32_e32 v26, v25, v24
	v_fma_f32 v27, -v21, v26, v25
	v_fmac_f32_e32 v26, v27, v24
	v_fma_f32 v21, -v21, v26, v25
	v_div_fmas_f32 v21, v21, v24, v26
	v_div_fixup_f32 v16, v21, v17, v16
	v_mul_f32_e32 v17, 0xbfb8aa3b, v14
	v_exp_f32_e32 v17, v17
	v_mul_f32_e32 v16, v19, v16
	v_mul_f32_e32 v16, v16, v20
	v_add_f32_e32 v17, 1.0, v17
	v_div_scale_f32 v19, s[4:5], v17, v17, v14
	v_rcp_f32_e32 v21, v19
	s_nop 0
	v_fma_f32 v24, -v19, v21, 1.0
	v_fmac_f32_e32 v21, v24, v21
	v_div_scale_f32 v24, vcc, v14, v17, v14
	v_mul_f32_e32 v25, v24, v21
	v_fma_f32 v26, -v19, v25, v24
	v_fmac_f32_e32 v25, v26, v21
	v_fma_f32 v19, -v19, v25, v24
	v_div_fmas_f32 v19, v19, v21, v25
	v_div_fixup_f32 v14, v19, v17, v14
	v_mul_f32_e32 v14, v23, v14
	v_mul_f32_e32 v14, v14, v20
	v_cvt_pk_bf16_f32 v14, v16, v14
	v_lshlrev_b32_e32 v16, 16, v15
	v_mul_f32_e32 v17, 0xbfb8aa3b, v16
	v_exp_f32_e32 v17, v17
	v_and_b32_e32 v15, 0xffff0000, v15
	v_add_f32_e32 v17, 1.0, v17
	v_div_scale_f32 v19, s[4:5], v17, v17, v16
	v_rcp_f32_e32 v21, v19
	s_nop 0
	v_fma_f32 v23, -v19, v21, 1.0
	v_fmac_f32_e32 v21, v23, v21
	v_div_scale_f32 v23, vcc, v16, v17, v16
	v_mul_f32_e32 v24, v23, v21
	v_fma_f32 v25, -v19, v24, v23
	v_fmac_f32_e32 v24, v25, v21
	v_fma_f32 v19, -v19, v24, v23
	v_div_fmas_f32 v19, v19, v21, v24
	v_div_fixup_f32 v16, v19, v17, v16
	v_mul_f32_e32 v17, 0xbfb8aa3b, v15
	v_exp_f32_e32 v17, v17
	v_mul_f32_e32 v16, v18, v16
	v_mul_f32_e32 v16, v16, v20
	v_add_f32_e32 v17, 1.0, v17
	v_div_scale_f32 v18, s[4:5], v17, v17, v15
	v_rcp_f32_e32 v19, v18
	s_nop 0
	v_fma_f32 v21, -v18, v19, 1.0
	v_fmac_f32_e32 v19, v21, v19
	v_div_scale_f32 v21, vcc, v15, v17, v15
	v_mul_f32_e32 v23, v21, v19
	v_fma_f32 v24, -v18, v23, v21
	v_fmac_f32_e32 v23, v24, v19
	v_fma_f32 v18, -v18, v23, v21
	v_div_fmas_f32 v18, v18, v19, v23
	v_div_fixup_f32 v15, v18, v17, v15
	v_mul_f32_e32 v15, v22, v15
	v_mul_f32_e32 v15, v15, v20
	v_cvt_pk_bf16_f32 v15, v16, v15
	v_lshlrev_b64 v[16:17], 13, v[80:81]
	v_lshl_add_u64 v[16:17], s[46:47], 0, v[16:17]
	v_lshl_add_u64 v[16:17], v[16:17], 0, v[82:83]
	v_lshl_add_u64 v[16:17], v[16:17], 0, v[74:75]
	global_store_dwordx4 v[16:17], v[12:15], off
	s_waitcnt vmcnt(7)
	v_lshlrev_b32_e32 v17, 16, v6
	v_lshlrev_b32_e32 v16, 16, v7
	s_waitcnt vmcnt(6)
	v_lshlrev_b32_e32 v12, 16, v8
	v_lshlrev_b32_e32 v14, 16, v4
	v_lshlrev_b32_e32 v13, 16, v9
	v_lshlrev_b32_e32 v15, 16, v5
	v_and_b32_e32 v8, 0xffff0000, v8
	v_and_b32_e32 v4, 0xffff0000, v4
	v_and_b32_e32 v9, 0xffff0000, v9
	v_and_b32_e32 v5, 0xffff0000, v5
	v_pk_add_f32 v[12:13], v[14:15], v[12:13]
	v_lshlrev_b32_e32 v15, 16, v10
	v_lshlrev_b32_e32 v14, 16, v11
	v_pk_add_f32 v[4:5], v[4:5], v[8:9]
	v_pk_mul_f32 v[8:9], v[12:13], v[12:13]
	v_and_b32_e32 v19, 0xffff0000, v10
	v_and_b32_e32 v21, 0xffff0000, v6
	v_and_b32_e32 v18, 0xffff0000, v11
	v_and_b32_e32 v20, 0xffff0000, v7
	v_pk_add_f32 v[6:7], v[16:17], v[14:15]
	v_pk_fma_f32 v[8:9], v[4:5], v[4:5], v[8:9]
	v_pk_add_f32 v[10:11], v[20:21], v[18:19]
	v_pk_mul_f32 v[14:15], v[6:7], v[6:7]
	v_add_f32_e32 v8, v8, v9
	v_pk_fma_f32 v[14:15], v[10:11], v[10:11], v[14:15]
	s_nop 0
	v_add_f32_e32 v8, v15, v8
	v_add_f32_e32 v8, v14, v8
	s_nop 1
	v_add_f32_dpp v8, v8, v8 row_ror:8 row_mask:0xf bank_mask:0xf bound_ctrl:1
	s_nop 1
	v_add_f32_dpp v8, v8, v8 row_ror:4 row_mask:0xf bank_mask:0xf bound_ctrl:1
	s_nop 1
	v_add_f32_dpp v8, v8, v8 row_ror:2 row_mask:0xf bank_mask:0xf bound_ctrl:1
	s_nop 1
	v_add_f32_dpp v8, v8, v8 row_ror:1 row_mask:0xf bank_mask:0xf bound_ctrl:1
	s_nop 0
	v_readlane_b32 s1, v8, 16
	v_readlane_b32 s2, v8, 48
	v_readlane_b32 s4, v8, 0
	v_readlane_b32 s5, v8, 32
	v_mov_b32_e32 v8, s1
	v_mov_b32_e32 v9, s2
	v_pk_add_f32 v[8:9], s[4:5], v[8:9]
	s_mul_i32 s2, s94, 48
	v_add_f32_e32 v8, v8, v9
	v_fmamk_f32 v8, v8, 0x3b000000, v173
	v_cmp_gt_f32_e32 vcc, s19, v8
	v_mul_f32_e32 v9, 0x4f800000, v8
	s_mul_i32 s1, s94, 0x6000
	v_cndmask_b32_e32 v8, v8, v9, vcc
	v_sqrt_f32_e32 v9, v8
	v_add_u32_e32 v73, s2, v73
	v_add_u32_e32 v94, s1, v94
	s_mov_b32 s1, 0x11fff
	v_add_u32_e32 v14, -1, v9
	v_fma_f32 v15, -v14, v9, v8
	v_cmp_ge_f32_e64 s[38:39], 0, v15
	v_add_u32_e32 v15, 1, v9
	s_nop 0
	v_cndmask_b32_e64 v14, v9, v14, s[38:39]
	v_fma_f32 v9, -v15, v9, v8
	v_cmp_lt_f32_e64 s[38:39], 0, v9
	s_nop 1
	v_cndmask_b32_e64 v9, v14, v15, s[38:39]
	v_mul_f32_e32 v14, 0x37800000, v9
	v_cndmask_b32_e32 v9, v9, v14, vcc
	v_cmp_class_f32_e32 vcc, v8, v244
	s_nop 1
	v_cndmask_b32_e32 v8, v9, v8, vcc
	v_div_scale_f32 v9, s[4:5], v8, v8, 1.0
	v_rcp_f32_e32 v14, v9
	s_nop 0
	v_fma_f32 v15, -v9, v14, 1.0
	v_fmac_f32_e32 v14, v15, v14
	v_div_scale_f32 v15, vcc, 1.0, v8, 1.0
	v_mul_f32_e32 v16, v15, v14
	v_fma_f32 v17, -v9, v16, v15
	v_fmac_f32_e32 v16, v17, v14
	v_fma_f32 v9, -v9, v16, v15
	v_div_fmas_f32 v9, v9, v14, v16
	v_div_fixup_f32 v8, v9, v8, 1.0
	s_waitcnt vmcnt(5)
	v_lshlrev_b32_e32 v9, 16, v0
	v_mul_f32_e32 v14, 0xbfb8aa3b, v9
	v_exp_f32_e32 v14, v14
	v_and_b32_e32 v0, 0xffff0000, v0
	v_add_f32_e32 v14, 1.0, v14
	v_div_scale_f32 v15, s[4:5], v14, v14, v9
	v_rcp_f32_e32 v16, v15
	s_nop 0
	v_fma_f32 v17, -v15, v16, 1.0
	v_fmac_f32_e32 v16, v17, v16
	v_div_scale_f32 v17, vcc, v9, v14, v9
	v_mul_f32_e32 v18, v17, v16
	v_fma_f32 v19, -v15, v18, v17
	v_fmac_f32_e32 v18, v19, v16
	v_fma_f32 v15, -v15, v18, v17
	v_div_fmas_f32 v15, v15, v16, v18
	v_div_fixup_f32 v9, v15, v14, v9
	v_mul_f32_e32 v9, v12, v9
	v_mul_f32_e32 v12, 0xbfb8aa3b, v0
	v_exp_f32_e32 v12, v12
	v_mul_f32_e32 v9, v9, v8
	v_add_f32_e32 v12, 1.0, v12
	v_div_scale_f32 v14, s[4:5], v12, v12, v0
	v_rcp_f32_e32 v15, v14
	s_nop 0
	v_fma_f32 v16, -v14, v15, 1.0
	v_fmac_f32_e32 v15, v16, v15
	v_div_scale_f32 v16, vcc, v0, v12, v0
	v_mul_f32_e32 v17, v16, v15
	v_fma_f32 v18, -v14, v17, v16
	v_fmac_f32_e32 v17, v18, v15
	v_fma_f32 v14, -v14, v17, v16
	v_div_fmas_f32 v14, v14, v15, v17
	v_div_fixup_f32 v0, v14, v12, v0
	v_mul_f32_e32 v0, v4, v0
	v_mul_f32_e32 v0, v0, v8
	v_lshlrev_b32_e32 v4, 16, v1
	v_cvt_pk_bf16_f32 v0, v9, v0
	v_mul_f32_e32 v9, 0xbfb8aa3b, v4
	v_exp_f32_e32 v9, v9
	v_and_b32_e32 v1, 0xffff0000, v1
	v_add_f32_e32 v9, 1.0, v9
	v_div_scale_f32 v12, s[4:5], v9, v9, v4
	v_rcp_f32_e32 v14, v12
	s_nop 0
	v_fma_f32 v15, -v12, v14, 1.0
	v_fmac_f32_e32 v14, v15, v14
	v_div_scale_f32 v15, vcc, v4, v9, v4
	v_mul_f32_e32 v16, v15, v14
	v_fma_f32 v17, -v12, v16, v15
	v_fmac_f32_e32 v16, v17, v14
	v_fma_f32 v12, -v12, v16, v15
	v_div_fmas_f32 v12, v12, v14, v16
	v_div_fixup_f32 v4, v12, v9, v4
	v_mul_f32_e32 v9, 0xbfb8aa3b, v1
	v_exp_f32_e32 v9, v9
	v_mul_f32_e32 v4, v13, v4
	v_mul_f32_e32 v4, v4, v8
	v_add_f32_e32 v9, 1.0, v9
	v_div_scale_f32 v12, s[4:5], v9, v9, v1
	v_rcp_f32_e32 v13, v12
	s_nop 0
	v_fma_f32 v14, -v12, v13, 1.0
	v_fmac_f32_e32 v13, v14, v13
	v_div_scale_f32 v14, vcc, v1, v9, v1
	v_mul_f32_e32 v15, v14, v13
	v_fma_f32 v16, -v12, v15, v14
	v_fmac_f32_e32 v15, v16, v13
	v_fma_f32 v12, -v12, v15, v14
	v_div_fmas_f32 v12, v12, v13, v15
	v_div_fixup_f32 v1, v12, v9, v1
	v_mul_f32_e32 v1, v5, v1
	v_mul_f32_e32 v1, v1, v8
	v_cvt_pk_bf16_f32 v1, v4, v1
	v_lshlrev_b32_e32 v4, 16, v2
	v_mul_f32_e32 v5, 0xbfb8aa3b, v4
	v_exp_f32_e32 v5, v5
	v_and_b32_e32 v2, 0xffff0000, v2
	v_add_f32_e32 v5, 1.0, v5
	v_div_scale_f32 v9, s[4:5], v5, v5, v4
	v_rcp_f32_e32 v12, v9
	s_nop 0
	v_fma_f32 v13, -v9, v12, 1.0
	v_fmac_f32_e32 v12, v13, v12
	v_div_scale_f32 v13, vcc, v4, v5, v4
	v_mul_f32_e32 v14, v13, v12
	v_fma_f32 v15, -v9, v14, v13
	v_fmac_f32_e32 v14, v15, v12
	v_fma_f32 v9, -v9, v14, v13
	v_div_fmas_f32 v9, v9, v12, v14
	v_div_fixup_f32 v4, v9, v5, v4
	v_mul_f32_e32 v5, 0xbfb8aa3b, v2
	v_exp_f32_e32 v5, v5
	v_mul_f32_e32 v4, v7, v4
	v_mul_f32_e32 v4, v4, v8
	v_add_f32_e32 v5, 1.0, v5
	v_div_scale_f32 v7, s[4:5], v5, v5, v2
	v_rcp_f32_e32 v9, v7
	s_nop 0
	v_fma_f32 v12, -v7, v9, 1.0
	v_fmac_f32_e32 v9, v12, v9
	v_div_scale_f32 v12, vcc, v2, v5, v2
	v_mul_f32_e32 v13, v12, v9
	v_fma_f32 v14, -v7, v13, v12
	v_fmac_f32_e32 v13, v14, v9
	v_fma_f32 v7, -v7, v13, v12
	v_div_fmas_f32 v7, v7, v9, v13
	v_div_fixup_f32 v2, v7, v5, v2
	v_mul_f32_e32 v2, v11, v2
	v_mul_f32_e32 v2, v2, v8
	v_cvt_pk_bf16_f32 v2, v4, v2
	v_lshlrev_b32_e32 v4, 16, v3
	v_mul_f32_e32 v5, 0xbfb8aa3b, v4
	v_exp_f32_e32 v5, v5
	v_and_b32_e32 v3, 0xffff0000, v3
	v_add_f32_e32 v5, 1.0, v5
	v_div_scale_f32 v7, s[4:5], v5, v5, v4
	v_rcp_f32_e32 v9, v7
	s_nop 0
	v_fma_f32 v11, -v7, v9, 1.0
	v_fmac_f32_e32 v9, v11, v9
	v_div_scale_f32 v11, vcc, v4, v5, v4
	v_mul_f32_e32 v12, v11, v9
	v_fma_f32 v13, -v7, v12, v11
	v_fmac_f32_e32 v12, v13, v9
	v_fma_f32 v7, -v7, v12, v11
	v_div_fmas_f32 v7, v7, v9, v12
	v_div_fixup_f32 v4, v7, v5, v4
	v_mul_f32_e32 v5, 0xbfb8aa3b, v3
	v_exp_f32_e32 v5, v5
	v_mul_f32_e32 v4, v6, v4
	v_mul_f32_e32 v4, v4, v8
	v_add_f32_e32 v5, 1.0, v5
	v_div_scale_f32 v6, s[4:5], v5, v5, v3
	v_rcp_f32_e32 v7, v6
	s_nop 0
	v_fma_f32 v9, -v6, v7, 1.0
	v_fmac_f32_e32 v7, v9, v7
	v_div_scale_f32 v9, vcc, v3, v5, v3
	v_mul_f32_e32 v11, v9, v7
	v_fma_f32 v12, -v6, v11, v9
	v_fmac_f32_e32 v11, v12, v7
	v_fma_f32 v6, -v6, v11, v9
	v_div_fmas_f32 v6, v6, v7, v11
	v_div_fixup_f32 v3, v6, v5, v3
	v_mul_f32_e32 v3, v10, v3
	v_mul_f32_e32 v3, v3, v8
	v_cvt_pk_bf16_f32 v3, v4, v3
	v_lshlrev_b64 v[4:5], 13, v[78:79]
	v_lshl_add_u64 v[4:5], s[46:47], 0, v[4:5]
	v_lshl_add_u64 v[4:5], v[4:5], 0, v[76:77]
	v_cmp_lt_i32_e32 vcc, s1, v73
	v_lshl_add_u64 v[4:5], v[4:5], 0, v[74:75]
	s_or_b64 s[50:51], vcc, s[50:51]
	global_store_dwordx4 v[4:5], v[0:3], off
	s_andn2_b64 exec, exec, s[50:51]
	s_cbranch_execnz .LBB0_405
